# speedup vs baseline: 1.0054x; 1.0054x over previous
; #define MFMA(a, b, c) __builtin_amdgcn_mfma_f32_16x16x32_bf16((a), (b), (c), 0, 0, 0)
; __device__ __forceinline__ void mla_attn_job(const Params& p, int half, int job, char* smem) {
;     ...
; #pragma unroll
;     for (int t = 0; t < QT; ++t) {
;       float ps = 0.f;
;       const float mr = mrun[t];
; #pragma unroll
;       for (int mt = 0; mt < 4; ++mt)
; #pragma unroll
;         for (int j = 0; j < 4; ++j) {
;           float e = __builtin_amdgcn_exp2f(sc[mt][t][j] - mr);
;           sc[mt][t][j] = e;
;           ps += e;
;         }
;       lrun[t] += ps;
; #pragma unroll
;       for (int tl = 0; tl < 2; ++tl) {
;         unsigned w0 = pack2(sc[2 * tl][t][0], sc[2 * tl][t][1]), w1 = pack2(sc[2 * tl][t][2], sc[2 * tl][t][3]);
;         unsigned w2 = pack2(sc[2 * tl + 1][t][0], sc[2 * tl + 1][t][1]), w3 = pack2(sc[2 * tl + 1][t][2], sc[2 * tl + 1][t][3]);
;         bf16x8 a;
;         a[0] = (short)(w0 & 0xffff); a[1] = (short)(w0 >> 16); a[2] = (short)(w1 & 0xffff); a[3] = (short)(w1 >> 16);
;         a[4] = (short)(w2 & 0xffff); a[5] = (short)(w2 >> 16); a[6] = (short)(w3 & 0xffff); a[7] = (short)(w3 >> 16);
;         pa[t][tl] = a;
;       }
;     }
;     __builtin_amdgcn_s_setprio(1);
; #pragma unroll
;     for (int tl = 0; tl < 2; ++tl)
; #pragma unroll
;       for (int n = 0; n < 4; ++n) {
;         bf16x8 b = *(const bf16x8*)(Vt + (n * 16 + fr) * 72 + tl * 32 + fq * 8);
; #pragma unroll
;         for (int t = 0; t < QT; ++t) oacc[t][n] = MFMA(pa[t][tl], b, oacc[t][n]);
;       }
;     __builtin_amdgcn_s_setprio(0);
.LBB0_222:
	v_add3_u32 v224, s26, v233, v232
	ds_read_b128 v[238:241], v224 offset:13312
	ds_read_b128 v[242:245], v224 offset:15616
	ds_read_b128 v[246:249], v224 offset:17920
	ds_read_b128 v[250:253], v224 offset:20224
	v_sub_f32_e32 v160, v160, v237
	v_sub_f32_e32 v161, v161, v237
	v_sub_f32_e32 v162, v162, v237
	v_sub_f32_e32 v163, v163, v237
	v_exp_f32_e32 v160, v160
	v_exp_f32_e32 v161, v161
	v_exp_f32_e32 v162, v162
	v_exp_f32_e32 v163, v163
	v_add_f32_e32 v228, v160, v161
	v_add_f32_e32 v228, v228, v162
	v_add_f32_e32 v228, v228, v163
	v_sub_f32_e32 v180, v180, v237
	v_sub_f32_e32 v181, v181, v237
	v_sub_f32_e32 v182, v182, v237
	v_sub_f32_e32 v183, v183, v237
	v_exp_f32_e32 v180, v180
	v_exp_f32_e32 v181, v181
	v_exp_f32_e32 v182, v182
	v_exp_f32_e32 v183, v183
	v_add_f32_e32 v228, v228, v180
	v_add_f32_e32 v228, v228, v181
	v_add_f32_e32 v228, v228, v182
	v_add_f32_e32 v228, v228, v183
	v_cvt_pk_bf16_f32 v160, v160, v161
	v_cvt_pk_bf16_f32 v161, v162, v163
	v_cvt_pk_bf16_f32 v162, v180, v181
	v_cvt_pk_bf16_f32 v163, v182, v183
	s_setprio 1
	s_waitcnt lgkmcnt(0)
	s_nop 1
	v_mfma_f32_16x16x32_bf16 v[96:99], v[160:163], v[238:241], v[96:99]
	v_sub_f32_e32 v156, v156, v236
	v_sub_f32_e32 v157, v157, v236
	v_sub_f32_e32 v158, v158, v236
	v_sub_f32_e32 v159, v159, v236
	v_exp_f32_e32 v156, v156
	v_exp_f32_e32 v157, v157
	v_exp_f32_e32 v158, v158
	v_mfma_f32_16x16x32_bf16 v[100:103], v[160:163], v[242:245], v[100:103]
	v_exp_f32_e32 v159, v159
	v_add_f32_e32 v229, v156, v157
	v_add_f32_e32 v229, v229, v158
	v_add_f32_e32 v229, v229, v159
	v_sub_f32_e32 v168, v168, v236
	v_sub_f32_e32 v169, v169, v236
	v_sub_f32_e32 v170, v170, v236
	v_mfma_f32_16x16x32_bf16 v[104:107], v[160:163], v[246:249], v[104:107]
	v_sub_f32_e32 v171, v171, v236
	v_exp_f32_e32 v168, v168
	v_exp_f32_e32 v169, v169
	v_exp_f32_e32 v170, v170
	v_exp_f32_e32 v171, v171
	v_add_f32_e32 v229, v229, v168
	v_add_f32_e32 v229, v229, v169
	v_mfma_f32_16x16x32_bf16 v[108:111], v[160:163], v[250:253], v[108:111]
	v_add_f32_e32 v229, v229, v170
	v_add_f32_e32 v229, v229, v171
	v_cvt_pk_bf16_f32 v156, v156, v157
	v_cvt_pk_bf16_f32 v157, v158, v159
	v_cvt_pk_bf16_f32 v158, v168, v169
	v_cvt_pk_bf16_f32 v159, v170, v171
	ds_read_b128 v[168:171], v224 offset:13376
	s_nop 1
	v_mfma_f32_16x16x32_bf16 v[32:35], v[156:159], v[238:241], v[32:35]
	v_sub_f32_e32 v136, v136, v235
	v_sub_f32_e32 v137, v137, v235
	v_sub_f32_e32 v138, v138, v235
	v_sub_f32_e32 v139, v139, v235
	v_exp_f32_e32 v136, v136
	v_exp_f32_e32 v137, v137
	v_exp_f32_e32 v138, v138
	v_mfma_f32_16x16x32_bf16 v[36:39], v[156:159], v[242:245], v[36:39]
	v_exp_f32_e32 v139, v139
	v_add_f32_e32 v230, v136, v137
	v_add_f32_e32 v230, v230, v138
	v_add_f32_e32 v230, v230, v139
	v_sub_f32_e32 v148, v148, v235
	v_sub_f32_e32 v149, v149, v235
	v_sub_f32_e32 v150, v150, v235
	v_mfma_f32_16x16x32_bf16 v[40:43], v[156:159], v[246:249], v[40:43]
	v_sub_f32_e32 v151, v151, v235
	v_exp_f32_e32 v148, v148
	v_exp_f32_e32 v149, v149
	v_exp_f32_e32 v150, v150
	v_exp_f32_e32 v151, v151
	v_add_f32_e32 v230, v230, v148
	v_add_f32_e32 v230, v230, v149
	v_mfma_f32_16x16x32_bf16 v[44:47], v[156:159], v[250:253], v[44:47]
	v_add_f32_e32 v230, v230, v150
	v_add_f32_e32 v230, v230, v151
	v_cvt_pk_bf16_f32 v136, v136, v137
	v_cvt_pk_bf16_f32 v137, v138, v139
	v_cvt_pk_bf16_f32 v138, v148, v149
	v_cvt_pk_bf16_f32 v139, v150, v151
	ds_read_b128 v[148:151], v224 offset:15680
	s_nop 1
	v_mfma_f32_16x16x32_bf16 v[16:19], v[136:139], v[238:241], v[16:19]
	v_sub_f32_e32 v132, v132, v234
	v_sub_f32_e32 v133, v133, v234
	v_sub_f32_e32 v134, v134, v234
	v_sub_f32_e32 v135, v135, v234
	v_exp_f32_e32 v132, v132
	v_exp_f32_e32 v133, v133
	v_exp_f32_e32 v134, v134
	v_mfma_f32_16x16x32_bf16 v[20:23], v[136:139], v[242:245], v[20:23]
	v_exp_f32_e32 v135, v135
	v_add_f32_e32 v180, v132, v133
	v_add_f32_e32 v180, v180, v134
	v_add_f32_e32 v180, v180, v135
	v_sub_f32_e32 v140, v140, v234
	v_sub_f32_e32 v141, v141, v234
	v_sub_f32_e32 v142, v142, v234
	v_mfma_f32_16x16x32_bf16 v[24:27], v[136:139], v[246:249], v[24:27]
	v_sub_f32_e32 v143, v143, v234
	v_exp_f32_e32 v140, v140
	v_exp_f32_e32 v141, v141
	v_exp_f32_e32 v142, v142
	v_exp_f32_e32 v143, v143
	v_add_f32_e32 v180, v180, v140
	v_add_f32_e32 v180, v180, v141
	v_mfma_f32_16x16x32_bf16 v[28:31], v[136:139], v[250:253], v[28:31]
	v_add_f32_e32 v180, v180, v142
	v_add_f32_e32 v180, v180, v143
	v_cvt_pk_bf16_f32 v132, v132, v133
	v_cvt_pk_bf16_f32 v133, v134, v135
	v_cvt_pk_bf16_f32 v134, v140, v141
	v_cvt_pk_bf16_f32 v135, v142, v143
	ds_read_b128 v[140:143], v224 offset:17984
	s_nop 1
	v_mfma_f32_16x16x32_bf16 v[0:3], v[132:135], v[238:241], v[0:3]
	ds_read_b128 v[238:241], v224 offset:20288
	v_sub_f32_e32 v184, v184, v237
	v_sub_f32_e32 v185, v185, v237
	v_sub_f32_e32 v186, v186, v237
	v_sub_f32_e32 v187, v187, v237
	v_exp_f32_e32 v184, v184
	v_exp_f32_e32 v185, v185
	v_exp_f32_e32 v186, v186
	v_exp_f32_e32 v187, v187
	v_mfma_f32_16x16x32_bf16 v[4:7], v[132:135], v[242:245], v[4:7]
	v_add_f32_e32 v228, v228, v184
	v_add_f32_e32 v228, v228, v185
	v_add_f32_e32 v228, v228, v186
	v_add_f32_e32 v228, v228, v187
	v_sub_f32_e32 v192, v192, v237
	v_sub_f32_e32 v193, v193, v237
	v_sub_f32_e32 v194, v194, v237
	v_sub_f32_e32 v195, v195, v237
	v_mfma_f32_16x16x32_bf16 v[8:11], v[132:135], v[246:249], v[8:11]
	v_exp_f32_e32 v192, v192
	v_exp_f32_e32 v193, v193
	v_exp_f32_e32 v194, v194
	v_exp_f32_e32 v195, v195
	v_add_f32_e32 v228, v228, v192
	v_add_f32_e32 v228, v228, v193
	v_add_f32_e32 v228, v228, v194
	v_add_f32_e32 v228, v228, v195
	v_mfma_f32_16x16x32_bf16 v[12:15], v[132:135], v[250:253], v[12:15]
	v_add_f32_e32 v205, v205, v228
	v_cvt_pk_bf16_f32 v184, v184, v185
	v_cvt_pk_bf16_f32 v185, v186, v187
	v_cvt_pk_bf16_f32 v186, v192, v193
	v_cvt_pk_bf16_f32 v187, v194, v195
	s_waitcnt lgkmcnt(0)
; #define MFMA(a, b, c) __builtin_amdgcn_mfma_f32_16x16x32_bf16((a), (b), (c), 0, 0, 0)
; __device__ __forceinline__ void mla_attn_job(const Params& p, int half, int job, char* smem) {
;     ...
; #pragma unroll
;     for (int t = 0; t < QT; ++t) {
;       float ps = 0.f;
;       const float mr = mrun[t];
; #pragma unroll
;       for (int mt = 0; mt < 4; ++mt)
; #pragma unroll
;         for (int j = 0; j < 4; ++j) {
;           float e = __builtin_amdgcn_exp2f(sc[mt][t][j] - mr);
;           sc[mt][t][j] = e;
;           ps += e;
;         }
;       lrun[t] += ps;
; #pragma unroll
;       for (int tl = 0; tl < 2; ++tl) {
;         unsigned w0 = pack2(sc[2 * tl][t][0], sc[2 * tl][t][1]), w1 = pack2(sc[2 * tl][t][2], sc[2 * tl][t][3]);
;         unsigned w2 = pack2(sc[2 * tl + 1][t][0], sc[2 * tl + 1][t][1]), w3 = pack2(sc[2 * tl + 1][t][2], sc[2 * tl + 1][t][3]);
;         bf16x8 a;
;         a[0] = (short)(w0 & 0xffff); a[1] = (short)(w0 >> 16); a[2] = (short)(w1 & 0xffff); a[3] = (short)(w1 >> 16);
;         a[4] = (short)(w2 & 0xffff); a[5] = (short)(w2 >> 16); a[6] = (short)(w3 & 0xffff); a[7] = (short)(w3 >> 16);
;         pa[t][tl] = a;
;       }
;     }
;     __builtin_amdgcn_s_setprio(1);
; #pragma unroll
;     for (int tl = 0; tl < 2; ++tl)
; #pragma unroll
;       for (int n = 0; n < 4; ++n) {
;         bf16x8 b = *(const bf16x8*)(Vt + (n * 16 + fr) * 72 + tl * 32 + fq * 8);
; #pragma unroll
;         for (int t = 0; t < QT; ++t) oacc[t][n] = MFMA(pa[t][tl], b, oacc[t][n]);
;       }
;     __builtin_amdgcn_s_setprio(0);
	s_nop 1
	v_mfma_f32_16x16x32_bf16 v[96:99], v[184:187], v[168:171], v[96:99]
	v_sub_f32_e32 v172, v172, v236
	v_sub_f32_e32 v173, v173, v236
	v_sub_f32_e32 v174, v174, v236
	v_sub_f32_e32 v175, v175, v236
	v_exp_f32_e32 v172, v172
	v_exp_f32_e32 v173, v173
	v_exp_f32_e32 v174, v174
	v_exp_f32_e32 v175, v175
	v_mfma_f32_16x16x32_bf16 v[100:103], v[184:187], v[148:151], v[100:103]
	v_add_f32_e32 v229, v229, v172
	v_add_f32_e32 v229, v229, v173
	v_add_f32_e32 v229, v229, v174
	v_add_f32_e32 v229, v229, v175
	v_sub_f32_e32 v188, v188, v236
	v_sub_f32_e32 v189, v189, v236
	v_sub_f32_e32 v190, v190, v236
	v_sub_f32_e32 v191, v191, v236
	v_mfma_f32_16x16x32_bf16 v[104:107], v[184:187], v[140:143], v[104:107]
	v_exp_f32_e32 v188, v188
	v_exp_f32_e32 v189, v189
	v_exp_f32_e32 v190, v190
	v_exp_f32_e32 v191, v191
	v_add_f32_e32 v229, v229, v188
	v_add_f32_e32 v229, v229, v189
	v_add_f32_e32 v229, v229, v190
	v_add_f32_e32 v229, v229, v191
	v_mfma_f32_16x16x32_bf16 v[108:111], v[184:187], v[238:241], v[108:111]
	v_add_f32_e32 v204, v204, v229
	v_cvt_pk_bf16_f32 v172, v172, v173
	v_cvt_pk_bf16_f32 v173, v174, v175
	v_cvt_pk_bf16_f32 v174, v188, v189
	v_cvt_pk_bf16_f32 v175, v190, v191
	s_nop 1
	v_mfma_f32_16x16x32_bf16 v[32:35], v[172:175], v[168:171], v[32:35]
	v_sub_f32_e32 v152, v152, v235
	v_sub_f32_e32 v153, v153, v235
	v_sub_f32_e32 v154, v154, v235
	v_sub_f32_e32 v155, v155, v235
	v_exp_f32_e32 v152, v152
	v_exp_f32_e32 v153, v153
	v_exp_f32_e32 v154, v154
	v_exp_f32_e32 v155, v155
	v_mfma_f32_16x16x32_bf16 v[36:39], v[172:175], v[148:151], v[36:39]
	v_add_f32_e32 v230, v230, v152
	v_add_f32_e32 v230, v230, v153
	v_add_f32_e32 v230, v230, v154
	v_add_f32_e32 v230, v230, v155
	v_sub_f32_e32 v176, v176, v235
	v_sub_f32_e32 v177, v177, v235
	v_sub_f32_e32 v178, v178, v235
	v_sub_f32_e32 v179, v179, v235
	v_mfma_f32_16x16x32_bf16 v[40:43], v[172:175], v[140:143], v[40:43]
	v_exp_f32_e32 v176, v176
	v_exp_f32_e32 v177, v177
	v_exp_f32_e32 v178, v178
	v_exp_f32_e32 v179, v179
	v_add_f32_e32 v230, v230, v176
	v_add_f32_e32 v230, v230, v177
	v_add_f32_e32 v230, v230, v178
	v_add_f32_e32 v230, v230, v179
	v_mfma_f32_16x16x32_bf16 v[44:47], v[172:175], v[238:241], v[44:47]
	v_add_f32_e32 v203, v203, v230
	v_cvt_pk_bf16_f32 v152, v152, v153
	v_cvt_pk_bf16_f32 v153, v154, v155
	v_cvt_pk_bf16_f32 v154, v176, v177
	v_cvt_pk_bf16_f32 v155, v178, v179
	s_nop 1
	v_mfma_f32_16x16x32_bf16 v[16:19], v[152:155], v[168:171], v[16:19]
	v_sub_f32_e32 v144, v144, v234
	v_sub_f32_e32 v145, v145, v234
	v_sub_f32_e32 v146, v146, v234
	v_sub_f32_e32 v147, v147, v234
	v_exp_f32_e32 v144, v144
	v_exp_f32_e32 v145, v145
	v_exp_f32_e32 v146, v146
	v_exp_f32_e32 v147, v147
	v_mfma_f32_16x16x32_bf16 v[20:23], v[152:155], v[148:151], v[20:23]
	v_add_f32_e32 v180, v180, v144
	v_add_f32_e32 v180, v180, v145
	v_add_f32_e32 v180, v180, v146
	v_add_f32_e32 v180, v180, v147
	v_sub_f32_e32 v164, v164, v234
	v_sub_f32_e32 v165, v165, v234
	v_sub_f32_e32 v166, v166, v234
	v_sub_f32_e32 v167, v167, v234
	v_mfma_f32_16x16x32_bf16 v[24:27], v[152:155], v[140:143], v[24:27]
	v_exp_f32_e32 v164, v164
	v_exp_f32_e32 v165, v165
	v_exp_f32_e32 v166, v166
	v_exp_f32_e32 v167, v167
	v_add_f32_e32 v180, v180, v164
	v_add_f32_e32 v180, v180, v165
	v_add_f32_e32 v180, v180, v166
	v_add_f32_e32 v180, v180, v167
	v_mfma_f32_16x16x32_bf16 v[28:31], v[152:155], v[238:241], v[28:31]
	v_add_f32_e32 v202, v202, v180
	v_cvt_pk_bf16_f32 v144, v144, v145
	v_cvt_pk_bf16_f32 v145, v146, v147
	v_cvt_pk_bf16_f32 v146, v164, v165
	v_cvt_pk_bf16_f32 v147, v166, v167
	s_nop 1
	v_mfma_f32_16x16x32_bf16 v[0:3], v[144:147], v[168:171], v[0:3]
	v_mfma_f32_16x16x32_bf16 v[4:7], v[144:147], v[148:151], v[4:7]
	v_mfma_f32_16x16x32_bf16 v[8:11], v[144:147], v[140:143], v[8:11]
	v_mfma_f32_16x16x32_bf16 v[12:15], v[144:147], v[238:241], v[12:15]
	s_setprio 0
	s_cmp_lg_u32 s11, s25
	v_readlane_b32 s66, v254, 4
	s_cbranch_scc0 .LBB0_220
